# v7 + Swiglu epilogues: row-sum shuffles via v_permlane16/32_swap instead of ds_bpermute round trips
# baseline (speedup 1.0000x reference)
.LBB0_635:
	v_mov_b32_e32 v128, v172
	v_mov_b32_e32 v129, v173
	s_lshl_b32 s0, s0, 8
	s_add_i32 s0, s0, s36
	v_lshlrev_b32_e32 v144, 3, v129
	v_add_u32_e32 v181, s0, v128
	v_ashrrev_i32_e32 v145, 31, v144
	v_lshlrev_b32_e32 v160, 5, v181
	v_lshl_add_u64 v[182:183], v[144:145], 2, s[76:77]
	v_lshl_add_u64 v[132:133], v[160:161], 2, v[182:183]
	v_add_u32_e32 v136, 0x200, v160
	v_mov_b32_e32 v137, v161
	global_load_dwordx4 v[128:131], v[132:133], off
	s_nop 0
	global_load_dwordx4 v[132:135], v[132:133], off offset:16
	v_lshl_add_u64 v[140:141], v[136:137], 2, v[182:183]
	global_load_dwordx4 v[136:139], v[140:141], off
	s_nop 0
	global_load_dwordx4 v[140:143], v[140:141], off offset:16
	v_and_b32_e32 v148, 64, v178
	s_lshl_b32 s0, s1, 7
	v_xor_b32_e32 v146, 16, v178
	v_add_u32_e32 v148, 64, v148
	s_or_b32 s0, s0, s37
	v_cmp_lt_i32_e32 vcc, v146, v148
	v_mov_b32_e32 v145, v161
	v_add_u32_e32 v170, s0, v144
	v_cndmask_b32_e32 v146, v178, v146, vcc
	v_add_u32_e32 v144, 0x400, v160
	v_mov_b32_e32 v147, v161
	v_mov_b32_e32 v187, v161
	v_lshlrev_b32_e32 v171, 2, v146
	v_add_u32_e32 v146, 0x600, v160
	v_add_u32_e32 v186, 0x1400, v160
	v_lshl_add_u64 v[144:145], v[144:145], 2, v[182:183]
	v_lshl_add_u64 v[146:147], v[146:147], 2, v[182:183]
	v_lshl_add_u64 v[212:213], v[186:187], 2, v[182:183]
	global_load_dwordx4 v[186:189], v[144:145], off
	global_load_dwordx4 v[190:193], v[144:145], off offset:16
	global_load_dwordx4 v[194:197], v[146:147], off
	global_load_dwordx4 v[198:201], v[146:147], off offset:16
	v_xor_b32_e32 v150, 32, v178
	v_cmp_lt_i32_e32 vcc, v150, v148
	v_mov_b32_e32 v149, v161
	v_mov_b32_e32 v151, v161
	v_cndmask_b32_e32 v148, v178, v150, vcc
	v_lshlrev_b32_e32 v214, 2, v148
	v_add_u32_e32 v148, 0x1000, v160
	v_add_u32_e32 v150, 0x1200, v160
	v_add_u32_e32 v160, 0x1600, v160
	v_lshl_add_u64 v[148:149], v[148:149], 2, v[182:183]
	v_lshl_add_u64 v[210:211], v[150:151], 2, v[182:183]
	global_load_dwordx4 v[220:223], v[148:149], off
	global_load_dwordx4 v[224:227], v[148:149], off offset:16
	global_load_dwordx4 v[228:231], v[210:211], off
	global_load_dwordx4 v[232:235], v[210:211], off offset:16
	global_load_dwordx4 v[236:239], v[212:213], off
	global_load_dwordx4 v[240:243], v[212:213], off offset:16
	v_lshl_add_u64 v[252:253], v[160:161], 2, v[182:183]
	global_load_dwordx4 v[244:247], v[252:253], off
	global_load_dwordx4 v[248:251], v[252:253], off offset:16
	v_pk_mul_f32 v[122:123], v[126:127], v[122:123]
	v_pk_mul_f32 v[120:121], v[124:125], v[120:121]
	v_pk_mul_f32 v[112:113], v[116:117], v[112:113]
	v_pk_mul_f32 v[114:115], v[118:119], v[114:115]
	v_pk_mul_f32 v[106:107], v[110:111], v[106:107]
	v_pk_mul_f32 v[104:105], v[108:109], v[104:105]
	v_pk_mul_f32 v[98:99], v[102:103], v[98:99]
	v_pk_mul_f32 v[96:97], v[100:101], v[96:97]
	v_pk_mul_f32 v[90:91], v[94:95], v[90:91]
	v_pk_mul_f32 v[88:89], v[92:93], v[88:89]
	v_pk_mul_f32 v[82:83], v[86:87], v[82:83]
	v_pk_mul_f32 v[80:81], v[84:85], v[80:81]
	v_pk_mul_f32 v[74:75], v[78:79], v[74:75]
	v_pk_mul_f32 v[72:73], v[76:77], v[72:73]
	v_pk_mul_f32 v[66:67], v[70:71], v[66:67]
	v_pk_mul_f32 v[64:65], v[68:69], v[64:65]
	v_pk_mul_f32 v[58:59], v[62:63], v[58:59]
	v_pk_mul_f32 v[56:57], v[60:61], v[56:57]
	v_pk_mul_f32 v[50:51], v[54:55], v[50:51]
	v_pk_mul_f32 v[48:49], v[52:53], v[48:49]
	v_pk_mul_f32 v[42:43], v[46:47], v[42:43]
	v_pk_mul_f32 v[40:41], v[44:45], v[40:41]
	v_pk_mul_f32 v[34:35], v[38:39], v[34:35]
	v_pk_mul_f32 v[32:33], v[36:37], v[32:33]
	v_pk_mul_f32 v[26:27], v[30:31], v[26:27]
	v_pk_mul_f32 v[24:25], v[28:29], v[24:25]
	v_pk_mul_f32 v[18:19], v[22:23], v[18:19]
	v_pk_mul_f32 v[16:17], v[20:21], v[16:17]
	v_pk_mul_f32 v[10:11], v[14:15], v[10:11]
	v_pk_mul_f32 v[8:9], v[12:13], v[8:9]
	v_pk_mul_f32 v[2:3], v[6:7], v[2:3]
	v_pk_mul_f32 v[0:1], v[4:5], v[0:1]
	s_waitcnt vmcnt(0)
	v_mov_b32_e32 v144, v128
	v_mov_b32_e32 v145, v132
	v_mov_b32_e32 v132, v129
	v_mov_b32_e32 v128, v130
	v_mov_b32_e32 v129, v134
	v_mov_b32_e32 v134, v131
	v_mov_b32_e32 v130, v136
	v_mov_b32_e32 v131, v140
	v_mov_b32_e32 v140, v137
	v_mov_b32_e32 v136, v138
	v_mov_b32_e32 v137, v142
	v_mov_b32_e32 v142, v139
	v_pk_add_f32 v[132:133], v[144:145], v[132:133]
	v_pk_add_f32 v[128:129], v[128:129], v[134:135]
	v_pk_add_f32 v[130:131], v[130:131], v[140:141]
	v_pk_add_f32 v[134:135], v[136:137], v[142:143]
	v_pk_add_f32 v[128:129], v[132:133], v[128:129]
	v_pk_add_f32 v[130:131], v[130:131], v[134:135]
	v_add_f32_e32 v128, v128, v129
	v_add_f32_e32 v129, v130, v131
	s_nop 0
	s_waitcnt lgkmcnt(0)
	v_mov_b32_e32 v130, v128
	v_mov_b32_e32 v253, v128
	s_nop 1
	v_permlane16_swap_b32_e32 v130, v253
	v_add_f32_e32 v130, v130, v253
	s_waitcnt lgkmcnt(0)
	v_mov_b32_e32 v131, v129
	v_mov_b32_e32 v253, v129
	s_nop 1
	v_permlane16_swap_b32_e32 v131, v253
	v_add_f32_e32 v131, v131, v253
	s_waitcnt lgkmcnt(0)
	v_mov_b32_e32 v132, v130
	v_mov_b32_e32 v253, v130
	s_nop 1
	v_permlane32_swap_b32_e32 v132, v253
	v_add_f32_e32 v130, v132, v253
	v_fmamk_f32 v130, v130, 0x3a000000, v179
	v_rsq_f32_e32 v202, v130
	s_waitcnt lgkmcnt(0)
	v_mov_b32_e32 v133, v131
	v_mov_b32_e32 v253, v131
	s_nop 1
	v_permlane32_swap_b32_e32 v133, v253
	v_add_f32_e32 v131, v133, v253
	v_fmamk_f32 v131, v131, 0x3a000000, v179
	v_rsq_f32_e32 v203, v131
	v_mov_b32_e32 v182, v186
	v_mov_b32_e32 v183, v190
	v_mov_b32_e32 v190, v187
	v_mov_b32_e32 v186, v188
	v_mov_b32_e32 v187, v192
	v_mov_b32_e32 v192, v189
	v_pk_add_f32 v[182:183], v[182:183], v[190:191]
	v_pk_add_f32 v[186:187], v[186:187], v[192:193]
	v_pk_add_f32 v[182:183], v[182:183], v[186:187]
	v_add_f32_e32 v182, v182, v183
	v_mov_b32_e32 v160, v202
	s_waitcnt lgkmcnt(0)
	v_mov_b32_e32 v183, v182
	v_mov_b32_e32 v253, v182
	s_nop 1
	v_permlane16_swap_b32_e32 v183, v253
	v_add_f32_e32 v182, v183, v253
	s_waitcnt lgkmcnt(0)
	v_mov_b32_e32 v183, v182
	v_mov_b32_e32 v253, v182
	s_nop 1
	v_permlane32_swap_b32_e32 v183, v253
	v_add_f32_e32 v182, v183, v253
	v_fmamk_f32 v182, v182, 0x3a000000, v179
	v_rsq_f32_e32 v204, v182
	v_mov_b32_e32 v186, v196
	v_mov_b32_e32 v187, v200
	v_mov_b32_e32 v182, v194
	v_mov_b32_e32 v183, v198
	v_mov_b32_e32 v198, v195
	v_mov_b32_e32 v200, v197
	v_pk_add_f32 v[182:183], v[182:183], v[198:199]
	v_pk_add_f32 v[186:187], v[186:187], v[200:201]
	v_pk_add_f32 v[182:183], v[182:183], v[186:187]
	v_add_f32_e32 v182, v182, v183
	v_mov_b32_e32 v188, v203
	s_waitcnt lgkmcnt(0)
	v_mov_b32_e32 v183, v182
	v_mov_b32_e32 v253, v182
	s_nop 1
	v_permlane16_swap_b32_e32 v183, v253
	v_add_f32_e32 v182, v183, v253
	s_waitcnt lgkmcnt(0)
	v_mov_b32_e32 v183, v182
	v_mov_b32_e32 v253, v182
	s_nop 1
	v_permlane32_swap_b32_e32 v183, v253
	v_add_f32_e32 v182, v183, v253
	v_fmamk_f32 v182, v182, 0x3a000000, v179
	v_rsq_f32_e32 v205, v182
	s_waitcnt vmcnt(7)
	v_mov_b32_e32 v186, v222
	s_waitcnt vmcnt(6)
	v_mov_b32_e32 v187, v226
	v_mov_b32_e32 v182, v220
	v_mov_b32_e32 v183, v224
	v_mov_b32_e32 v224, v221
	v_mov_b32_e32 v226, v223
	v_pk_add_f32 v[182:183], v[182:183], v[224:225]
	v_pk_add_f32 v[186:187], v[186:187], v[226:227]
	v_pk_add_f32 v[182:183], v[182:183], v[186:187]
	v_add_f32_e32 v182, v182, v183
	s_waitcnt lgkmcnt(0)
	v_mov_b32_e32 v183, v182
	v_mov_b32_e32 v253, v182
	s_nop 1
	v_permlane16_swap_b32_e32 v183, v253
	v_add_f32_e32 v182, v183, v253
	v_mov_b32_e32 v186, v204
	s_waitcnt lgkmcnt(0)
	v_mov_b32_e32 v183, v182
	v_mov_b32_e32 v253, v182
	s_nop 1
	v_permlane32_swap_b32_e32 v183, v253
	v_add_f32_e32 v182, v183, v253
	v_fmamk_f32 v182, v182, 0x3a000000, v179
	v_rsq_f32_e32 v206, v182
	s_waitcnt vmcnt(5)
	v_mov_b32_e32 v182, v228
	s_waitcnt vmcnt(4)
	v_mov_b32_e32 v183, v232
	v_mov_b32_e32 v232, v229
	v_mov_b32_e32 v228, v230
	v_mov_b32_e32 v229, v234
	v_mov_b32_e32 v234, v231
	v_pk_add_f32 v[232:233], v[182:183], v[232:233]
	v_pk_add_f32 v[234:235], v[228:229], v[234:235]
	v_pk_add_f32 v[232:233], v[232:233], v[234:235]
	v_add_f32_e32 v232, v232, v233
	s_waitcnt lgkmcnt(0)
	v_mov_b32_e32 v233, v232
	v_mov_b32_e32 v253, v232
	s_nop 1
	v_permlane16_swap_b32_e32 v233, v253
	v_add_f32_e32 v232, v233, v253
	s_waitcnt lgkmcnt(0)
	v_mov_b32_e32 v233, v232
	v_mov_b32_e32 v253, v232
	s_nop 1
	v_permlane32_swap_b32_e32 v233, v253
	v_add_f32_e32 v232, v233, v253
	v_fmamk_f32 v232, v232, 0x3a000000, v179
	v_rsq_f32_e32 v207, v232
	v_mov_b32_e32 v234, v205
	s_waitcnt vmcnt(3)
	v_mov_b32_e32 v232, v236
	s_waitcnt vmcnt(2)
	v_mov_b32_e32 v233, v240
	v_mov_b32_e32 v240, v237
	v_mov_b32_e32 v236, v238
	v_mov_b32_e32 v237, v242
	v_mov_b32_e32 v242, v239
	v_pk_add_f32 v[240:241], v[232:233], v[240:241]
	v_pk_add_f32 v[242:243], v[236:237], v[242:243]
	v_pk_add_f32 v[240:241], v[240:241], v[242:243]
	v_add_f32_e32 v240, v240, v241
	s_waitcnt lgkmcnt(0)
	v_mov_b32_e32 v241, v240
	v_mov_b32_e32 v253, v240
	s_nop 1
	v_permlane16_swap_b32_e32 v241, v253
	v_add_f32_e32 v240, v241, v253
	s_waitcnt lgkmcnt(0)
	v_mov_b32_e32 v241, v240
	v_mov_b32_e32 v253, v240
	s_nop 1
	v_permlane32_swap_b32_e32 v241, v253
	v_add_f32_e32 v240, v241, v253
	v_fmamk_f32 v240, v240, 0x3a000000, v179
	v_rsq_f32_e32 v208, v240
	v_mov_b32_e32 v242, v206
	s_waitcnt vmcnt(1)
	v_mov_b32_e32 v240, v244
	s_waitcnt vmcnt(0)
	v_mov_b32_e32 v241, v248
	v_mov_b32_e32 v248, v245
	v_mov_b32_e32 v244, v246
	v_mov_b32_e32 v245, v250
	v_mov_b32_e32 v250, v247
	v_pk_add_f32 v[248:249], v[240:241], v[248:249]
	v_pk_add_f32 v[250:251], v[244:245], v[250:251]
	v_pk_add_f32 v[248:249], v[248:249], v[250:251]
	v_add_f32_e32 v248, v248, v249
	v_mov_b32_e32 v251, v207
	s_waitcnt lgkmcnt(0)
	v_mov_b32_e32 v249, v248
	v_mov_b32_e32 v253, v248
	s_nop 1
	v_permlane16_swap_b32_e32 v249, v253
	v_add_f32_e32 v248, v249, v253
	s_waitcnt lgkmcnt(0)
	v_mov_b32_e32 v249, v248
	v_mov_b32_e32 v253, v248
	s_nop 1
	v_permlane32_swap_b32_e32 v249, v253
	v_add_f32_e32 v248, v249, v253
	v_fmamk_f32 v248, v248, 0x3a000000, v179
	v_rsq_f32_e32 v209, v248
	v_mov_b32_e32 v243, v208
	v_ashrrev_i32_e32 v171, 31, v170
	v_mul_f32_e32 v250, 0xbfb8aa3b, v160
	v_pk_mul_f32 v[240:241], v[124:125], v[250:251] op_sel_hi:[1,0]
	v_mov_b32_e32 v248, v209
	v_exp_f32_e32 v249, v240
	v_pk_mul_f32 v[246:247], v[126:127], v[250:251] op_sel_hi:[1,0]
	v_exp_f32_e32 v245, v241
	v_exp_f32_e32 v240, v246
	v_exp_f32_e32 v241, v247
	v_add_f32_e32 v249, 1.0, v249
	v_rcp_f32_e32 v246, v249
	v_add_f32_e32 v249, 1.0, v245
	v_rcp_f32_e32 v247, v249
	v_add_f32_e32 v249, 1.0, v240
	v_pk_mul_f32 v[126:127], v[116:117], v[250:251] op_sel_hi:[1,0]
	v_rcp_f32_e32 v240, v249
	v_add_f32_e32 v249, 1.0, v241
	v_pk_mul_f32 v[124:125], v[118:119], v[250:251] op_sel_hi:[1,0]
	v_exp_f32_e32 v126, v126
	v_exp_f32_e32 v127, v127
	v_rcp_f32_e32 v241, v249
	v_exp_f32_e32 v249, v124
	v_exp_f32_e32 v250, v125
	v_add_f32_e32 v124, 1.0, v126
	v_add_f32_e32 v125, 1.0, v127
	v_rcp_f32_e32 v124, v124
	v_rcp_f32_e32 v125, v125
	v_add_f32_e32 v126, 1.0, v249
	v_add_f32_e32 v127, 1.0, v250
	v_rcp_f32_e32 v126, v126
	v_rcp_f32_e32 v127, v127
	v_mul_f32_e32 v244, v160, v160
	v_pk_mul_f32 v[112:113], v[112:113], v[244:245] op_sel_hi:[1,0]
	v_pk_mul_f32 v[120:121], v[120:121], v[244:245] op_sel_hi:[1,0]
	v_pk_mul_f32 v[122:123], v[122:123], v[244:245] op_sel_hi:[1,0]
	v_pk_mul_f32 v[114:115], v[114:115], v[244:245] op_sel_hi:[1,0]
	v_pk_mul_f32 v[112:113], v[112:113], v[124:125]
	v_pk_mul_f32 v[122:123], v[122:123], v[240:241]
	v_pk_mul_f32 v[120:121], v[120:121], v[246:247]
	v_pk_mul_f32 v[114:115], v[114:115], v[126:127]
	v_cvt_pk_bf16_f32 v116, v120, v121
	v_cvt_pk_bf16_f32 v117, v122, v123
	v_cvt_pk_bf16_f32 v118, v112, v113
	v_mov_b64_e32 v[112:113], s[68:69]
	v_cvt_pk_bf16_f32 v119, v114, v115
	v_mad_i64_i32 v[120:121], s[0:1], v181, s45, v[112:113]
	v_lshlrev_b64 v[114:115], 1, v[170:171]
	v_lshl_add_u64 v[120:121], v[120:121], 0, v[114:115]
	global_store_dwordx4 v[120:121], v[116:119], off
	s_andn2_b64 vcc, exec, s[4:5]
	s_nop 0
	v_mul_f32_e32 v116, 0xbfb8aa3b, v188
	v_pk_mul_f32 v[122:123], v[108:109], v[116:117] op_sel_hi:[1,0]
	v_pk_mul_f32 v[120:121], v[110:111], v[116:117] op_sel_hi:[1,0]
	v_exp_f32_e32 v117, v122
	v_exp_f32_e32 v119, v123
	v_exp_f32_e32 v122, v120
	v_exp_f32_e32 v123, v121
	v_add_f32_e32 v117, 1.0, v117
	v_rcp_f32_e32 v120, v117
	v_add_f32_e32 v117, 1.0, v119
	v_rcp_f32_e32 v121, v117
	v_add_f32_e32 v117, 1.0, v122
	v_rcp_f32_e32 v122, v117
	v_add_f32_e32 v117, 1.0, v123
	v_pk_mul_f32 v[108:109], v[102:103], v[116:117] op_sel_hi:[1,0]
	v_pk_mul_f32 v[110:111], v[100:101], v[116:117] op_sel_hi:[1,0]
	v_rcp_f32_e32 v123, v117
	v_exp_f32_e32 v110, v110
	v_exp_f32_e32 v111, v111
	v_exp_f32_e32 v116, v108
	v_exp_f32_e32 v117, v109
	v_add_f32_e32 v108, 1.0, v110
	v_add_f32_e32 v109, 1.0, v111
	v_add_f32_e32 v110, 1.0, v116
	v_add_f32_e32 v111, 1.0, v117
	v_rcp_f32_e32 v108, v108
	v_rcp_f32_e32 v109, v109
	v_rcp_f32_e32 v110, v110
	v_rcp_f32_e32 v111, v111
	v_mul_f32_e32 v118, v188, v188
	v_pk_mul_f32 v[96:97], v[96:97], v[118:119] op_sel_hi:[1,0]
	v_pk_mul_f32 v[98:99], v[98:99], v[118:119] op_sel_hi:[1,0]
	v_pk_mul_f32 v[104:105], v[104:105], v[118:119] op_sel_hi:[1,0]
	v_pk_mul_f32 v[106:107], v[106:107], v[118:119] op_sel_hi:[1,0]
	v_pk_mul_f32 v[100:101], v[98:99], v[110:111]
	v_pk_mul_f32 v[98:99], v[96:97], v[108:109]
	v_add_u32_e32 v102, 16, v181
	v_pk_mul_f32 v[106:107], v[106:107], v[122:123]
	v_pk_mul_f32 v[104:105], v[104:105], v[120:121]
	s_nop 0
	v_cvt_pk_bf16_f32 v96, v104, v105
	v_cvt_pk_bf16_f32 v97, v106, v107
	v_cvt_pk_bf16_f32 v98, v98, v99
	v_cvt_pk_bf16_f32 v99, v100, v101
	v_mad_i64_i32 v[100:101], s[0:1], v102, s45, v[112:113]
	v_lshl_add_u64 v[100:101], v[100:101], 0, v[114:115]
	global_store_dwordx4 v[100:101], v[96:99], off
	s_nop 1
	v_mul_f32_e32 v96, 0xbfb8aa3b, v186
	v_pk_mul_f32 v[102:103], v[92:93], v[96:97] op_sel_hi:[1,0]
	v_pk_mul_f32 v[100:101], v[94:95], v[96:97] op_sel_hi:[1,0]
	v_exp_f32_e32 v97, v102
	v_exp_f32_e32 v99, v103
	v_exp_f32_e32 v102, v100
	v_exp_f32_e32 v103, v101
	v_add_f32_e32 v97, 1.0, v97
	v_rcp_f32_e32 v100, v97
	v_add_f32_e32 v97, 1.0, v99
	v_rcp_f32_e32 v101, v97
	v_add_f32_e32 v97, 1.0, v102
	v_rcp_f32_e32 v102, v97
	v_add_f32_e32 v97, 1.0, v103
	v_pk_mul_f32 v[92:93], v[86:87], v[96:97] op_sel_hi:[1,0]
	v_pk_mul_f32 v[94:95], v[84:85], v[96:97] op_sel_hi:[1,0]
	v_rcp_f32_e32 v103, v97
	v_exp_f32_e32 v94, v94
	v_exp_f32_e32 v95, v95
	v_exp_f32_e32 v96, v92
	v_exp_f32_e32 v97, v93
	v_add_f32_e32 v92, 1.0, v94
	v_add_f32_e32 v93, 1.0, v95
	v_add_f32_e32 v94, 1.0, v96
	v_add_f32_e32 v95, 1.0, v97
	v_rcp_f32_e32 v92, v92
	v_rcp_f32_e32 v93, v93
	v_rcp_f32_e32 v94, v94
	v_rcp_f32_e32 v95, v95
	v_mul_f32_e32 v98, v186, v186
	v_pk_mul_f32 v[80:81], v[80:81], v[98:99] op_sel_hi:[1,0]
	v_pk_mul_f32 v[82:83], v[82:83], v[98:99] op_sel_hi:[1,0]
	v_pk_mul_f32 v[88:89], v[88:89], v[98:99] op_sel_hi:[1,0]
	v_pk_mul_f32 v[90:91], v[90:91], v[98:99] op_sel_hi:[1,0]
	v_pk_mul_f32 v[84:85], v[82:83], v[94:95]
	v_pk_mul_f32 v[82:83], v[80:81], v[92:93]
	v_add_u32_e32 v86, 32, v181
	v_pk_mul_f32 v[90:91], v[90:91], v[102:103]
	v_pk_mul_f32 v[88:89], v[88:89], v[100:101]
	s_nop 0
	v_cvt_pk_bf16_f32 v80, v88, v89
	v_cvt_pk_bf16_f32 v81, v90, v91
	v_cvt_pk_bf16_f32 v82, v82, v83
	v_cvt_pk_bf16_f32 v83, v84, v85
	v_mad_i64_i32 v[84:85], s[0:1], v86, s45, v[112:113]
	v_lshl_add_u64 v[84:85], v[84:85], 0, v[114:115]
	global_store_dwordx4 v[84:85], v[80:83], off
	s_nop 1
	v_mul_f32_e32 v80, 0xbfb8aa3b, v234
	v_pk_mul_f32 v[86:87], v[76:77], v[80:81] op_sel_hi:[1,0]
	v_pk_mul_f32 v[84:85], v[78:79], v[80:81] op_sel_hi:[1,0]
	v_exp_f32_e32 v81, v86
	v_exp_f32_e32 v83, v87
	v_exp_f32_e32 v86, v84
	v_exp_f32_e32 v87, v85
	v_add_f32_e32 v81, 1.0, v81
	v_rcp_f32_e32 v84, v81
	v_add_f32_e32 v81, 1.0, v83
	v_rcp_f32_e32 v85, v81
	v_add_f32_e32 v81, 1.0, v86
	v_rcp_f32_e32 v86, v81
	v_add_f32_e32 v81, 1.0, v87
	v_pk_mul_f32 v[76:77], v[70:71], v[80:81] op_sel_hi:[1,0]
	v_pk_mul_f32 v[78:79], v[68:69], v[80:81] op_sel_hi:[1,0]
	v_rcp_f32_e32 v87, v81
	v_exp_f32_e32 v78, v78
	v_exp_f32_e32 v79, v79
	v_exp_f32_e32 v80, v76
	v_exp_f32_e32 v81, v77
	v_add_f32_e32 v76, 1.0, v78
	v_add_f32_e32 v77, 1.0, v79
	v_add_f32_e32 v78, 1.0, v80
	v_add_f32_e32 v79, 1.0, v81
	v_rcp_f32_e32 v76, v76
	v_rcp_f32_e32 v77, v77
	v_rcp_f32_e32 v78, v78
	v_rcp_f32_e32 v79, v79
	v_mul_f32_e32 v82, v234, v234
	v_pk_mul_f32 v[64:65], v[64:65], v[82:83] op_sel_hi:[1,0]
	v_pk_mul_f32 v[66:67], v[66:67], v[82:83] op_sel_hi:[1,0]
	v_pk_mul_f32 v[72:73], v[72:73], v[82:83] op_sel_hi:[1,0]
	v_pk_mul_f32 v[74:75], v[74:75], v[82:83] op_sel_hi:[1,0]
	v_pk_mul_f32 v[68:69], v[66:67], v[78:79]
	v_pk_mul_f32 v[66:67], v[64:65], v[76:77]
	v_add_u32_e32 v70, 48, v181
	v_pk_mul_f32 v[74:75], v[74:75], v[86:87]
	v_pk_mul_f32 v[72:73], v[72:73], v[84:85]
	s_nop 0
	v_cvt_pk_bf16_f32 v64, v72, v73
	v_cvt_pk_bf16_f32 v65, v74, v75
	v_cvt_pk_bf16_f32 v66, v66, v67
	v_cvt_pk_bf16_f32 v67, v68, v69
	v_mad_i64_i32 v[68:69], s[0:1], v70, s45, v[112:113]
	v_lshl_add_u64 v[68:69], v[68:69], 0, v[114:115]
	global_store_dwordx4 v[68:69], v[64:67], off
	s_nop 1
	v_add_u32_e32 v65, 0x80, v181
	v_mul_f32_e32 v64, 0xbfb8aa3b, v242
	v_pk_mul_f32 v[70:71], v[60:61], v[64:65] op_sel_hi:[1,0]
	v_pk_mul_f32 v[68:69], v[62:63], v[64:65] op_sel_hi:[1,0]
	v_exp_f32_e32 v67, v70
	v_exp_f32_e32 v70, v71
	v_exp_f32_e32 v71, v68
	v_exp_f32_e32 v72, v69
	v_add_f32_e32 v67, 1.0, v67
	v_rcp_f32_e32 v68, v67
	v_add_f32_e32 v67, 1.0, v70
	v_rcp_f32_e32 v69, v67
	v_add_f32_e32 v67, 1.0, v71
	v_mul_f32_e32 v66, v242, v242
	v_rcp_f32_e32 v70, v67
	v_add_f32_e32 v67, 1.0, v72
	v_pk_mul_f32 v[60:61], v[54:55], v[64:65] op_sel_hi:[1,0]
	v_pk_mul_f32 v[62:63], v[52:53], v[64:65] op_sel_hi:[1,0]
	v_rcp_f32_e32 v71, v67
	v_pk_mul_f32 v[56:57], v[56:57], v[66:67] op_sel_hi:[1,0]
	v_pk_mul_f32 v[58:59], v[58:59], v[66:67] op_sel_hi:[1,0]
	v_exp_f32_e32 v62, v62
	v_exp_f32_e32 v63, v63
	v_exp_f32_e32 v64, v60
	v_exp_f32_e32 v67, v61
	v_add_f32_e32 v60, 1.0, v62
	v_add_f32_e32 v61, 1.0, v63
	v_add_f32_e32 v62, 1.0, v64
	v_add_f32_e32 v63, 1.0, v67
	v_rcp_f32_e32 v60, v60
	v_rcp_f32_e32 v61, v61
	v_rcp_f32_e32 v62, v62
	v_rcp_f32_e32 v63, v63
	v_pk_mul_f32 v[48:49], v[48:49], v[66:67] op_sel_hi:[1,0]
	v_pk_mul_f32 v[50:51], v[50:51], v[66:67] op_sel_hi:[1,0]
	v_pk_mul_f32 v[58:59], v[58:59], v[70:71]
	v_pk_mul_f32 v[52:53], v[50:51], v[62:63]
	v_pk_mul_f32 v[50:51], v[48:49], v[60:61]
	v_pk_mul_f32 v[56:57], v[56:57], v[68:69]
	s_nop 0
	v_cvt_pk_bf16_f32 v48, v56, v57
	v_cvt_pk_bf16_f32 v49, v58, v59
	v_cvt_pk_bf16_f32 v50, v50, v51
	v_cvt_pk_bf16_f32 v51, v52, v53
	v_mad_i64_i32 v[52:53], s[0:1], v65, s45, v[112:113]
	v_lshl_add_u64 v[52:53], v[52:53], 0, v[114:115]
	global_store_dwordx4 v[52:53], v[48:51], off
	s_nop 1
	v_mul_f32_e32 v48, 0xbfb8aa3b, v251
	v_pk_mul_f32 v[54:55], v[44:45], v[48:49] op_sel_hi:[1,0]
	v_pk_mul_f32 v[52:53], v[46:47], v[48:49] op_sel_hi:[1,0]
	v_exp_f32_e32 v49, v54
	v_exp_f32_e32 v51, v55
	v_exp_f32_e32 v54, v52
	v_exp_f32_e32 v55, v53
	v_add_f32_e32 v49, 1.0, v49
	v_rcp_f32_e32 v52, v49
	v_add_f32_e32 v49, 1.0, v51
	v_rcp_f32_e32 v53, v49
	v_add_f32_e32 v49, 1.0, v54
	v_rcp_f32_e32 v54, v49
	v_add_f32_e32 v49, 1.0, v55
	v_pk_mul_f32 v[44:45], v[38:39], v[48:49] op_sel_hi:[1,0]
	v_pk_mul_f32 v[46:47], v[36:37], v[48:49] op_sel_hi:[1,0]
	v_rcp_f32_e32 v55, v49
	v_exp_f32_e32 v46, v46
	v_exp_f32_e32 v47, v47
	v_exp_f32_e32 v48, v44
	v_exp_f32_e32 v49, v45
	v_add_f32_e32 v44, 1.0, v46
	v_add_f32_e32 v45, 1.0, v47
	v_add_f32_e32 v46, 1.0, v48
	v_add_f32_e32 v47, 1.0, v49
	v_rcp_f32_e32 v44, v44
	v_rcp_f32_e32 v45, v45
	v_rcp_f32_e32 v46, v46
	v_rcp_f32_e32 v47, v47
	v_mul_f32_e32 v50, v251, v251
	v_pk_mul_f32 v[32:33], v[32:33], v[50:51] op_sel_hi:[1,0]
	v_pk_mul_f32 v[34:35], v[34:35], v[50:51] op_sel_hi:[1,0]
	v_pk_mul_f32 v[40:41], v[40:41], v[50:51] op_sel_hi:[1,0]
	v_pk_mul_f32 v[42:43], v[42:43], v[50:51] op_sel_hi:[1,0]
	v_pk_mul_f32 v[36:37], v[34:35], v[46:47]
	v_pk_mul_f32 v[34:35], v[32:33], v[44:45]
	v_add_u32_e32 v38, 0x90, v181
	v_pk_mul_f32 v[42:43], v[42:43], v[54:55]
	v_pk_mul_f32 v[40:41], v[40:41], v[52:53]
	s_nop 0
	v_cvt_pk_bf16_f32 v32, v40, v41
	v_cvt_pk_bf16_f32 v33, v42, v43
	v_cvt_pk_bf16_f32 v34, v34, v35
	v_cvt_pk_bf16_f32 v35, v36, v37
	v_mad_i64_i32 v[36:37], s[0:1], v38, s45, v[112:113]
	v_lshl_add_u64 v[36:37], v[36:37], 0, v[114:115]
	global_store_dwordx4 v[36:37], v[32:35], off
	s_nop 1
	v_mul_f32_e32 v32, 0xbfb8aa3b, v243
	v_pk_mul_f32 v[38:39], v[28:29], v[32:33] op_sel_hi:[1,0]
	v_pk_mul_f32 v[36:37], v[30:31], v[32:33] op_sel_hi:[1,0]
	v_exp_f32_e32 v33, v38
	v_exp_f32_e32 v35, v39
	v_exp_f32_e32 v38, v36
	v_exp_f32_e32 v39, v37
	v_add_f32_e32 v33, 1.0, v33
	v_rcp_f32_e32 v36, v33
	v_add_f32_e32 v33, 1.0, v35
	v_rcp_f32_e32 v37, v33
	v_add_f32_e32 v33, 1.0, v38
	v_rcp_f32_e32 v38, v33
	v_add_f32_e32 v33, 1.0, v39
	v_pk_mul_f32 v[28:29], v[22:23], v[32:33] op_sel_hi:[1,0]
	v_pk_mul_f32 v[30:31], v[20:21], v[32:33] op_sel_hi:[1,0]
	v_rcp_f32_e32 v39, v33
	v_exp_f32_e32 v30, v30
	v_exp_f32_e32 v31, v31
	v_exp_f32_e32 v32, v28
	v_exp_f32_e32 v33, v29
	v_add_f32_e32 v28, 1.0, v30
	v_add_f32_e32 v29, 1.0, v31
	v_add_f32_e32 v30, 1.0, v32
	v_add_f32_e32 v31, 1.0, v33
	v_rcp_f32_e32 v28, v28
	v_rcp_f32_e32 v29, v29
	v_rcp_f32_e32 v30, v30
	v_rcp_f32_e32 v31, v31
	v_mul_f32_e32 v34, v243, v243
	v_pk_mul_f32 v[16:17], v[16:17], v[34:35] op_sel_hi:[1,0]
	v_pk_mul_f32 v[18:19], v[18:19], v[34:35] op_sel_hi:[1,0]
	v_pk_mul_f32 v[24:25], v[24:25], v[34:35] op_sel_hi:[1,0]
	v_pk_mul_f32 v[26:27], v[26:27], v[34:35] op_sel_hi:[1,0]
	v_pk_mul_f32 v[20:21], v[18:19], v[30:31]
	v_pk_mul_f32 v[18:19], v[16:17], v[28:29]
	v_add_u32_e32 v22, 0xa0, v181
	v_pk_mul_f32 v[26:27], v[26:27], v[38:39]
	v_pk_mul_f32 v[24:25], v[24:25], v[36:37]
	s_nop 0
	v_cvt_pk_bf16_f32 v16, v24, v25
	v_cvt_pk_bf16_f32 v17, v26, v27
	v_cvt_pk_bf16_f32 v18, v18, v19
	v_cvt_pk_bf16_f32 v19, v20, v21
	v_mad_i64_i32 v[20:21], s[0:1], v22, s45, v[112:113]
	v_lshl_add_u64 v[20:21], v[20:21], 0, v[114:115]
	global_store_dwordx4 v[20:21], v[16:19], off
	s_nop 1
	v_mul_f32_e32 v16, 0xbfb8aa3b, v248
	v_pk_mul_f32 v[22:23], v[12:13], v[16:17] op_sel_hi:[1,0]
	v_pk_mul_f32 v[20:21], v[14:15], v[16:17] op_sel_hi:[1,0]
	v_exp_f32_e32 v17, v22
	v_exp_f32_e32 v19, v23
	v_exp_f32_e32 v22, v20
	v_exp_f32_e32 v23, v21
	v_add_f32_e32 v17, 1.0, v17
	v_rcp_f32_e32 v20, v17
	v_add_f32_e32 v17, 1.0, v19
	v_rcp_f32_e32 v21, v17
	v_add_f32_e32 v17, 1.0, v22
	v_rcp_f32_e32 v22, v17
	v_add_f32_e32 v17, 1.0, v23
	v_pk_mul_f32 v[12:13], v[6:7], v[16:17] op_sel_hi:[1,0]
	v_pk_mul_f32 v[14:15], v[4:5], v[16:17] op_sel_hi:[1,0]
	v_rcp_f32_e32 v23, v17
	v_exp_f32_e32 v14, v14
	v_exp_f32_e32 v15, v15
	v_exp_f32_e32 v16, v12
	v_exp_f32_e32 v17, v13
	v_add_f32_e32 v12, 1.0, v14
	v_add_f32_e32 v13, 1.0, v15
	v_add_f32_e32 v14, 1.0, v16
	v_add_f32_e32 v15, 1.0, v17
	v_rcp_f32_e32 v12, v12
	v_rcp_f32_e32 v13, v13
	v_rcp_f32_e32 v14, v14
	v_rcp_f32_e32 v15, v15
	v_mul_f32_e32 v18, v248, v248
	v_pk_mul_f32 v[0:1], v[0:1], v[18:19] op_sel_hi:[1,0]
	v_pk_mul_f32 v[2:3], v[2:3], v[18:19] op_sel_hi:[1,0]
	v_pk_mul_f32 v[8:9], v[8:9], v[18:19] op_sel_hi:[1,0]
	v_pk_mul_f32 v[10:11], v[10:11], v[18:19] op_sel_hi:[1,0]
	v_pk_mul_f32 v[4:5], v[2:3], v[14:15]
	v_pk_mul_f32 v[2:3], v[0:1], v[12:13]
	v_add_u32_e32 v6, 0xb0, v181
	v_pk_mul_f32 v[10:11], v[10:11], v[22:23]
	v_pk_mul_f32 v[8:9], v[8:9], v[20:21]
	s_nop 0
	v_cvt_pk_bf16_f32 v0, v8, v9
	v_cvt_pk_bf16_f32 v1, v10, v11
	v_cvt_pk_bf16_f32 v2, v2, v3
	v_cvt_pk_bf16_f32 v3, v4, v5
	v_mad_i64_i32 v[4:5], s[0:1], v6, s45, v[112:113]
	v_lshl_add_u64 v[4:5], v[4:5], 0, v[114:115]
	s_mov_b64 s[0:1], -1
	global_store_dwordx4 v[4:5], v[0:3], off
	s_cbranch_vccnz .LBB0_628
	s_andn2_b64 vcc, exec, s[8:9]
	s_cbranch_vccnz .LBB0_627
	s_barrier
	s_branch .LBB0_627

.LBB0_1367:
	v_mov_b32_e32 v128, v173
	v_mov_b32_e32 v129, v172
	s_lshl_b32 s0, s0, 8
	s_add_i32 s0, s0, s35
	v_lshlrev_b32_e32 v144, 3, v128
	v_add_u32_e32 v181, s0, v129
	v_ashrrev_i32_e32 v145, 31, v144
	v_lshlrev_b32_e32 v160, 5, v181
	v_lshl_add_u64 v[182:183], v[144:145], 2, s[76:77]
	v_lshl_add_u64 v[132:133], v[160:161], 2, v[182:183]
	v_add_u32_e32 v136, 0x200, v160
	v_mov_b32_e32 v137, v161
	global_load_dwordx4 v[128:131], v[132:133], off
	s_nop 0
	global_load_dwordx4 v[132:135], v[132:133], off offset:16
	v_lshl_add_u64 v[140:141], v[136:137], 2, v[182:183]
	global_load_dwordx4 v[136:139], v[140:141], off
	s_nop 0
	global_load_dwordx4 v[140:143], v[140:141], off offset:16
	v_and_b32_e32 v148, 64, v178
	s_lshl_b32 s0, s1, 7
	v_xor_b32_e32 v146, 16, v178
	v_add_u32_e32 v148, 64, v148
	s_or_b32 s0, s0, s36
	v_cmp_lt_i32_e32 vcc, v146, v148
	v_mov_b32_e32 v145, v161
	v_add_u32_e32 v170, s0, v144
	v_cndmask_b32_e32 v146, v178, v146, vcc
	v_add_u32_e32 v144, 0x400, v160
	v_mov_b32_e32 v147, v161
	v_mov_b32_e32 v187, v161
	v_lshlrev_b32_e32 v171, 2, v146
	v_add_u32_e32 v146, 0x600, v160
	v_add_u32_e32 v186, 0x1400, v160
	v_lshl_add_u64 v[144:145], v[144:145], 2, v[182:183]
	v_lshl_add_u64 v[146:147], v[146:147], 2, v[182:183]
	v_lshl_add_u64 v[212:213], v[186:187], 2, v[182:183]
	global_load_dwordx4 v[186:189], v[144:145], off
	global_load_dwordx4 v[190:193], v[144:145], off offset:16
	global_load_dwordx4 v[194:197], v[146:147], off
	global_load_dwordx4 v[198:201], v[146:147], off offset:16
	v_xor_b32_e32 v150, 32, v178
	v_cmp_lt_i32_e32 vcc, v150, v148
	v_mov_b32_e32 v149, v161
	v_mov_b32_e32 v151, v161
	v_cndmask_b32_e32 v148, v178, v150, vcc
	v_lshlrev_b32_e32 v185, 2, v148
	v_add_u32_e32 v148, 0x1000, v160
	v_add_u32_e32 v150, 0x1200, v160
	v_add_u32_e32 v160, 0x1600, v160
	v_lshl_add_u64 v[148:149], v[148:149], 2, v[182:183]
	v_lshl_add_u64 v[210:211], v[150:151], 2, v[182:183]
	global_load_dwordx4 v[220:223], v[148:149], off
	global_load_dwordx4 v[224:227], v[148:149], off offset:16
	global_load_dwordx4 v[228:231], v[210:211], off
	global_load_dwordx4 v[232:235], v[210:211], off offset:16
	global_load_dwordx4 v[236:239], v[212:213], off
	global_load_dwordx4 v[240:243], v[212:213], off offset:16
	v_lshl_add_u64 v[252:253], v[160:161], 2, v[182:183]
	global_load_dwordx4 v[244:247], v[252:253], off
	global_load_dwordx4 v[248:251], v[252:253], off offset:16
	v_pk_mul_f32 v[122:123], v[126:127], v[122:123]
	v_pk_mul_f32 v[120:121], v[124:125], v[120:121]
	v_pk_mul_f32 v[112:113], v[116:117], v[112:113]
	v_pk_mul_f32 v[114:115], v[118:119], v[114:115]
	v_pk_mul_f32 v[106:107], v[110:111], v[106:107]
	v_pk_mul_f32 v[104:105], v[108:109], v[104:105]
	v_pk_mul_f32 v[98:99], v[102:103], v[98:99]
	v_pk_mul_f32 v[96:97], v[100:101], v[96:97]
	v_pk_mul_f32 v[90:91], v[94:95], v[90:91]
	v_pk_mul_f32 v[88:89], v[92:93], v[88:89]
	v_pk_mul_f32 v[82:83], v[86:87], v[82:83]
	v_pk_mul_f32 v[80:81], v[84:85], v[80:81]
	v_pk_mul_f32 v[74:75], v[78:79], v[74:75]
	v_pk_mul_f32 v[72:73], v[76:77], v[72:73]
	v_pk_mul_f32 v[66:67], v[70:71], v[66:67]
	v_pk_mul_f32 v[64:65], v[68:69], v[64:65]
	v_pk_mul_f32 v[58:59], v[62:63], v[58:59]
	v_pk_mul_f32 v[56:57], v[60:61], v[56:57]
	v_pk_mul_f32 v[50:51], v[54:55], v[50:51]
	v_pk_mul_f32 v[48:49], v[52:53], v[48:49]
	v_pk_mul_f32 v[42:43], v[46:47], v[42:43]
	v_pk_mul_f32 v[40:41], v[44:45], v[40:41]
	v_pk_mul_f32 v[34:35], v[38:39], v[34:35]
	v_pk_mul_f32 v[32:33], v[36:37], v[32:33]
	v_pk_mul_f32 v[26:27], v[30:31], v[26:27]
	v_pk_mul_f32 v[24:25], v[28:29], v[24:25]
	v_pk_mul_f32 v[18:19], v[22:23], v[18:19]
	v_pk_mul_f32 v[16:17], v[20:21], v[16:17]
	v_pk_mul_f32 v[10:11], v[14:15], v[10:11]
	v_pk_mul_f32 v[8:9], v[12:13], v[8:9]
	v_pk_mul_f32 v[2:3], v[6:7], v[2:3]
	v_pk_mul_f32 v[0:1], v[4:5], v[0:1]
	s_waitcnt vmcnt(0)
	v_mov_b32_e32 v144, v128
	v_mov_b32_e32 v145, v132
	v_mov_b32_e32 v132, v129
	v_mov_b32_e32 v128, v130
	v_mov_b32_e32 v129, v134
	v_mov_b32_e32 v134, v131
	v_mov_b32_e32 v130, v136
	v_mov_b32_e32 v131, v140
	v_mov_b32_e32 v140, v137
	v_mov_b32_e32 v136, v138
	v_mov_b32_e32 v137, v142
	v_mov_b32_e32 v142, v139
	v_pk_add_f32 v[132:133], v[144:145], v[132:133]
	v_pk_add_f32 v[128:129], v[128:129], v[134:135]
	v_pk_add_f32 v[130:131], v[130:131], v[140:141]
	v_pk_add_f32 v[134:135], v[136:137], v[142:143]
	v_pk_add_f32 v[128:129], v[132:133], v[128:129]
	v_pk_add_f32 v[130:131], v[130:131], v[134:135]
	v_add_f32_e32 v128, v128, v129
	v_add_f32_e32 v129, v130, v131
	s_nop 0
	s_waitcnt lgkmcnt(0)
	v_mov_b32_e32 v130, v128
	v_mov_b32_e32 v253, v128
	s_nop 1
	v_permlane16_swap_b32_e32 v130, v253
	v_add_f32_e32 v130, v130, v253
	s_waitcnt lgkmcnt(0)
	v_mov_b32_e32 v131, v129
	v_mov_b32_e32 v253, v129
	s_nop 1
	v_permlane16_swap_b32_e32 v131, v253
	v_add_f32_e32 v131, v131, v253
	s_waitcnt lgkmcnt(0)
	v_mov_b32_e32 v132, v130
	v_mov_b32_e32 v253, v130
	s_nop 1
	v_permlane32_swap_b32_e32 v132, v253
	v_add_f32_e32 v130, v132, v253
	v_fmamk_f32 v130, v130, 0x3a000000, v179
	v_rsq_f32_e32 v202, v130
	s_waitcnt lgkmcnt(0)
	v_mov_b32_e32 v133, v131
	v_mov_b32_e32 v253, v131
	s_nop 1
	v_permlane32_swap_b32_e32 v133, v253
	v_add_f32_e32 v131, v133, v253
	v_fmamk_f32 v131, v131, 0x3a000000, v179
	v_rsq_f32_e32 v203, v131
	v_mov_b32_e32 v182, v186
	v_mov_b32_e32 v183, v190
	v_mov_b32_e32 v190, v187
	v_mov_b32_e32 v186, v188
	v_mov_b32_e32 v187, v192
	v_mov_b32_e32 v192, v189
	v_pk_add_f32 v[182:183], v[182:183], v[190:191]
	v_pk_add_f32 v[186:187], v[186:187], v[192:193]
	v_pk_add_f32 v[182:183], v[182:183], v[186:187]
	v_add_f32_e32 v182, v182, v183
	v_mov_b32_e32 v160, v202
	s_waitcnt lgkmcnt(0)
	v_mov_b32_e32 v183, v182
	v_mov_b32_e32 v253, v182
	s_nop 1
	v_permlane16_swap_b32_e32 v183, v253
	v_add_f32_e32 v182, v183, v253
	s_waitcnt lgkmcnt(0)
	v_mov_b32_e32 v183, v182
	v_mov_b32_e32 v253, v182
	s_nop 1
	v_permlane32_swap_b32_e32 v183, v253
	v_add_f32_e32 v182, v183, v253
	v_fmamk_f32 v182, v182, 0x3a000000, v179
	v_rsq_f32_e32 v204, v182
	v_mov_b32_e32 v186, v196
	v_mov_b32_e32 v187, v200
	v_mov_b32_e32 v182, v194
	v_mov_b32_e32 v183, v198
	v_mov_b32_e32 v198, v195
	v_mov_b32_e32 v200, v197
	v_pk_add_f32 v[182:183], v[182:183], v[198:199]
	v_pk_add_f32 v[186:187], v[186:187], v[200:201]
	v_pk_add_f32 v[182:183], v[182:183], v[186:187]
	v_add_f32_e32 v182, v182, v183
	v_mov_b32_e32 v188, v203
	s_waitcnt lgkmcnt(0)
	v_mov_b32_e32 v183, v182
	v_mov_b32_e32 v253, v182
	s_nop 1
	v_permlane16_swap_b32_e32 v183, v253
	v_add_f32_e32 v182, v183, v253
	s_waitcnt lgkmcnt(0)
	v_mov_b32_e32 v183, v182
	v_mov_b32_e32 v253, v182
	s_nop 1
	v_permlane32_swap_b32_e32 v183, v253
	v_add_f32_e32 v182, v183, v253
	v_fmamk_f32 v182, v182, 0x3a000000, v179
	v_rsq_f32_e32 v205, v182
	s_waitcnt vmcnt(7)
	v_mov_b32_e32 v186, v222
	s_waitcnt vmcnt(6)
	v_mov_b32_e32 v187, v226
	v_mov_b32_e32 v182, v220
	v_mov_b32_e32 v183, v224
	v_mov_b32_e32 v224, v221
	v_mov_b32_e32 v226, v223
	v_pk_add_f32 v[182:183], v[182:183], v[224:225]
	v_pk_add_f32 v[186:187], v[186:187], v[226:227]
	v_pk_add_f32 v[182:183], v[182:183], v[186:187]
	v_add_f32_e32 v182, v182, v183
	s_waitcnt lgkmcnt(0)
	v_mov_b32_e32 v183, v182
	v_mov_b32_e32 v253, v182
	s_nop 1
	v_permlane16_swap_b32_e32 v183, v253
	v_add_f32_e32 v182, v183, v253
	v_mov_b32_e32 v186, v204
	s_waitcnt lgkmcnt(0)
	v_mov_b32_e32 v183, v182
	v_mov_b32_e32 v253, v182
	s_nop 1
	v_permlane32_swap_b32_e32 v183, v253
	v_add_f32_e32 v182, v183, v253
	v_fmamk_f32 v182, v182, 0x3a000000, v179
	v_rsq_f32_e32 v206, v182
	s_waitcnt vmcnt(5)
	v_mov_b32_e32 v182, v228
	s_waitcnt vmcnt(4)
	v_mov_b32_e32 v183, v232
	v_mov_b32_e32 v232, v229
	v_mov_b32_e32 v228, v230
	v_mov_b32_e32 v229, v234
	v_mov_b32_e32 v234, v231
	v_pk_add_f32 v[232:233], v[182:183], v[232:233]
	v_pk_add_f32 v[234:235], v[228:229], v[234:235]
	v_pk_add_f32 v[232:233], v[232:233], v[234:235]
	v_add_f32_e32 v232, v232, v233
	s_waitcnt lgkmcnt(0)
	v_mov_b32_e32 v233, v232
	v_mov_b32_e32 v253, v232
	s_nop 1
	v_permlane16_swap_b32_e32 v233, v253
	v_add_f32_e32 v232, v233, v253
	s_waitcnt lgkmcnt(0)
	v_mov_b32_e32 v233, v232
	v_mov_b32_e32 v253, v232
	s_nop 1
	v_permlane32_swap_b32_e32 v233, v253
	v_add_f32_e32 v232, v233, v253
	v_fmamk_f32 v232, v232, 0x3a000000, v179
	v_rsq_f32_e32 v207, v232
	v_mov_b32_e32 v234, v205
	s_waitcnt vmcnt(3)
	v_mov_b32_e32 v232, v236
	s_waitcnt vmcnt(2)
	v_mov_b32_e32 v233, v240
	v_mov_b32_e32 v240, v237
	v_mov_b32_e32 v236, v238
	v_mov_b32_e32 v237, v242
	v_mov_b32_e32 v242, v239
	v_pk_add_f32 v[240:241], v[232:233], v[240:241]
	v_pk_add_f32 v[242:243], v[236:237], v[242:243]
	v_pk_add_f32 v[240:241], v[240:241], v[242:243]
	v_add_f32_e32 v240, v240, v241
	s_waitcnt lgkmcnt(0)
	v_mov_b32_e32 v241, v240
	v_mov_b32_e32 v253, v240
	s_nop 1
	v_permlane16_swap_b32_e32 v241, v253
	v_add_f32_e32 v240, v241, v253
	s_waitcnt lgkmcnt(0)
	v_mov_b32_e32 v241, v240
	v_mov_b32_e32 v253, v240
	s_nop 1
	v_permlane32_swap_b32_e32 v241, v253
	v_add_f32_e32 v240, v241, v253
	v_fmamk_f32 v240, v240, 0x3a000000, v179
	v_rsq_f32_e32 v208, v240
	v_mov_b32_e32 v242, v206
	s_waitcnt vmcnt(1)
	v_mov_b32_e32 v240, v244
	s_waitcnt vmcnt(0)
	v_mov_b32_e32 v241, v248
	v_mov_b32_e32 v248, v245
	v_mov_b32_e32 v244, v246
	v_mov_b32_e32 v245, v250
	v_mov_b32_e32 v250, v247
	v_pk_add_f32 v[248:249], v[240:241], v[248:249]
	v_pk_add_f32 v[250:251], v[244:245], v[250:251]
	v_pk_add_f32 v[248:249], v[248:249], v[250:251]
	v_add_f32_e32 v248, v248, v249
	v_mov_b32_e32 v251, v207
	s_waitcnt lgkmcnt(0)
	v_mov_b32_e32 v249, v248
	v_mov_b32_e32 v253, v248
	s_nop 1
	v_permlane16_swap_b32_e32 v249, v253
	v_add_f32_e32 v248, v249, v253
	s_waitcnt lgkmcnt(0)
	v_mov_b32_e32 v249, v248
	v_mov_b32_e32 v253, v248
	s_nop 1
	v_permlane32_swap_b32_e32 v249, v253
	v_add_f32_e32 v248, v249, v253
	v_fmamk_f32 v248, v248, 0x3a000000, v179
	v_rsq_f32_e32 v209, v248
	v_mov_b32_e32 v243, v208
	v_ashrrev_i32_e32 v171, 31, v170
	v_mul_f32_e32 v250, 0xbfb8aa3b, v160
	v_pk_mul_f32 v[240:241], v[124:125], v[250:251] op_sel_hi:[1,0]
	v_mov_b32_e32 v248, v209
	v_exp_f32_e32 v249, v240
	v_pk_mul_f32 v[246:247], v[126:127], v[250:251] op_sel_hi:[1,0]
	v_exp_f32_e32 v245, v241
	v_exp_f32_e32 v240, v246
	v_exp_f32_e32 v241, v247
	v_add_f32_e32 v249, 1.0, v249
	v_rcp_f32_e32 v246, v249
	v_add_f32_e32 v249, 1.0, v245
	v_rcp_f32_e32 v247, v249
	v_add_f32_e32 v249, 1.0, v240
	v_pk_mul_f32 v[126:127], v[116:117], v[250:251] op_sel_hi:[1,0]
	v_rcp_f32_e32 v240, v249
	v_add_f32_e32 v249, 1.0, v241
	v_pk_mul_f32 v[124:125], v[118:119], v[250:251] op_sel_hi:[1,0]
	v_exp_f32_e32 v126, v126
	v_exp_f32_e32 v127, v127
	v_rcp_f32_e32 v241, v249
	v_exp_f32_e32 v249, v124
	v_exp_f32_e32 v250, v125
	v_add_f32_e32 v124, 1.0, v126
	v_add_f32_e32 v125, 1.0, v127
	v_rcp_f32_e32 v124, v124
	v_rcp_f32_e32 v125, v125
	v_add_f32_e32 v126, 1.0, v249
	v_add_f32_e32 v127, 1.0, v250
	v_rcp_f32_e32 v126, v126
	v_rcp_f32_e32 v127, v127
	v_mul_f32_e32 v244, v160, v160
	v_pk_mul_f32 v[112:113], v[112:113], v[244:245] op_sel_hi:[1,0]
	v_pk_mul_f32 v[120:121], v[120:121], v[244:245] op_sel_hi:[1,0]
	v_pk_mul_f32 v[122:123], v[122:123], v[244:245] op_sel_hi:[1,0]
	v_pk_mul_f32 v[114:115], v[114:115], v[244:245] op_sel_hi:[1,0]
	v_pk_mul_f32 v[112:113], v[112:113], v[124:125]
	v_pk_mul_f32 v[122:123], v[122:123], v[240:241]
	v_pk_mul_f32 v[120:121], v[120:121], v[246:247]
	v_pk_mul_f32 v[114:115], v[114:115], v[126:127]
	v_cvt_pk_bf16_f32 v116, v120, v121
	v_cvt_pk_bf16_f32 v117, v122, v123
	v_cvt_pk_bf16_f32 v118, v112, v113
	v_mov_b64_e32 v[112:113], s[68:69]
	v_cvt_pk_bf16_f32 v119, v114, v115
	v_mad_i64_i32 v[120:121], s[0:1], v181, s44, v[112:113]
	v_lshlrev_b64 v[114:115], 1, v[170:171]
	v_lshl_add_u64 v[120:121], v[120:121], 0, v[114:115]
	global_store_dwordx4 v[120:121], v[116:119], off
	s_andn2_b64 vcc, exec, s[4:5]
	s_nop 0
	v_mul_f32_e32 v116, 0xbfb8aa3b, v188
	v_pk_mul_f32 v[122:123], v[108:109], v[116:117] op_sel_hi:[1,0]
	v_pk_mul_f32 v[120:121], v[110:111], v[116:117] op_sel_hi:[1,0]
	v_exp_f32_e32 v117, v122
	v_exp_f32_e32 v119, v123
	v_exp_f32_e32 v122, v120
	v_exp_f32_e32 v123, v121
	v_add_f32_e32 v117, 1.0, v117
	v_rcp_f32_e32 v120, v117
	v_add_f32_e32 v117, 1.0, v119
	v_rcp_f32_e32 v121, v117
	v_add_f32_e32 v117, 1.0, v122
	v_rcp_f32_e32 v122, v117
	v_add_f32_e32 v117, 1.0, v123
	v_pk_mul_f32 v[108:109], v[102:103], v[116:117] op_sel_hi:[1,0]
	v_pk_mul_f32 v[110:111], v[100:101], v[116:117] op_sel_hi:[1,0]
	v_rcp_f32_e32 v123, v117
	v_exp_f32_e32 v110, v110
	v_exp_f32_e32 v111, v111
	v_exp_f32_e32 v116, v108
	v_exp_f32_e32 v117, v109
	v_add_f32_e32 v108, 1.0, v110
	v_add_f32_e32 v109, 1.0, v111
	v_add_f32_e32 v110, 1.0, v116
	v_add_f32_e32 v111, 1.0, v117
	v_rcp_f32_e32 v108, v108
	v_rcp_f32_e32 v109, v109
	v_rcp_f32_e32 v110, v110
	v_rcp_f32_e32 v111, v111
	v_mul_f32_e32 v118, v188, v188
	v_pk_mul_f32 v[96:97], v[96:97], v[118:119] op_sel_hi:[1,0]
	v_pk_mul_f32 v[98:99], v[98:99], v[118:119] op_sel_hi:[1,0]
	v_pk_mul_f32 v[104:105], v[104:105], v[118:119] op_sel_hi:[1,0]
	v_pk_mul_f32 v[106:107], v[106:107], v[118:119] op_sel_hi:[1,0]
	v_pk_mul_f32 v[100:101], v[98:99], v[110:111]
	v_pk_mul_f32 v[98:99], v[96:97], v[108:109]
	v_add_u32_e32 v102, 16, v181
	v_pk_mul_f32 v[106:107], v[106:107], v[122:123]
	v_pk_mul_f32 v[104:105], v[104:105], v[120:121]
	s_nop 0
	v_cvt_pk_bf16_f32 v96, v104, v105
	v_cvt_pk_bf16_f32 v97, v106, v107
	v_cvt_pk_bf16_f32 v98, v98, v99
	v_cvt_pk_bf16_f32 v99, v100, v101
	v_mad_i64_i32 v[100:101], s[0:1], v102, s44, v[112:113]
	v_lshl_add_u64 v[100:101], v[100:101], 0, v[114:115]
	global_store_dwordx4 v[100:101], v[96:99], off
	s_nop 1
	v_mul_f32_e32 v96, 0xbfb8aa3b, v186
	v_pk_mul_f32 v[102:103], v[92:93], v[96:97] op_sel_hi:[1,0]
	v_pk_mul_f32 v[100:101], v[94:95], v[96:97] op_sel_hi:[1,0]
	v_exp_f32_e32 v97, v102
	v_exp_f32_e32 v99, v103
	v_exp_f32_e32 v102, v100
	v_exp_f32_e32 v103, v101
	v_add_f32_e32 v97, 1.0, v97
	v_rcp_f32_e32 v100, v97
	v_add_f32_e32 v97, 1.0, v99
	v_rcp_f32_e32 v101, v97
	v_add_f32_e32 v97, 1.0, v102
	v_rcp_f32_e32 v102, v97
	v_add_f32_e32 v97, 1.0, v103
	v_pk_mul_f32 v[92:93], v[86:87], v[96:97] op_sel_hi:[1,0]
	v_pk_mul_f32 v[94:95], v[84:85], v[96:97] op_sel_hi:[1,0]
	v_rcp_f32_e32 v103, v97
	v_exp_f32_e32 v94, v94
	v_exp_f32_e32 v95, v95
	v_exp_f32_e32 v96, v92
	v_exp_f32_e32 v97, v93
	v_add_f32_e32 v92, 1.0, v94
	v_add_f32_e32 v93, 1.0, v95
	v_add_f32_e32 v94, 1.0, v96
	v_add_f32_e32 v95, 1.0, v97
	v_rcp_f32_e32 v92, v92
	v_rcp_f32_e32 v93, v93
	v_rcp_f32_e32 v94, v94
	v_rcp_f32_e32 v95, v95
	v_mul_f32_e32 v98, v186, v186
	v_pk_mul_f32 v[80:81], v[80:81], v[98:99] op_sel_hi:[1,0]
	v_pk_mul_f32 v[82:83], v[82:83], v[98:99] op_sel_hi:[1,0]
	v_pk_mul_f32 v[88:89], v[88:89], v[98:99] op_sel_hi:[1,0]
	v_pk_mul_f32 v[90:91], v[90:91], v[98:99] op_sel_hi:[1,0]
	v_pk_mul_f32 v[84:85], v[82:83], v[94:95]
	v_pk_mul_f32 v[82:83], v[80:81], v[92:93]
	v_add_u32_e32 v86, 32, v181
	v_pk_mul_f32 v[90:91], v[90:91], v[102:103]
	v_pk_mul_f32 v[88:89], v[88:89], v[100:101]
	s_nop 0
	v_cvt_pk_bf16_f32 v80, v88, v89
	v_cvt_pk_bf16_f32 v81, v90, v91
	v_cvt_pk_bf16_f32 v82, v82, v83
	v_cvt_pk_bf16_f32 v83, v84, v85
	v_mad_i64_i32 v[84:85], s[0:1], v86, s44, v[112:113]
	v_lshl_add_u64 v[84:85], v[84:85], 0, v[114:115]
	global_store_dwordx4 v[84:85], v[80:83], off
	s_nop 1
	v_mul_f32_e32 v80, 0xbfb8aa3b, v234
	v_pk_mul_f32 v[86:87], v[76:77], v[80:81] op_sel_hi:[1,0]
	v_pk_mul_f32 v[84:85], v[78:79], v[80:81] op_sel_hi:[1,0]
	v_exp_f32_e32 v81, v86
	v_exp_f32_e32 v83, v87
	v_exp_f32_e32 v86, v84
	v_exp_f32_e32 v87, v85
	v_add_f32_e32 v81, 1.0, v81
	v_rcp_f32_e32 v84, v81
	v_add_f32_e32 v81, 1.0, v83
	v_rcp_f32_e32 v85, v81
	v_add_f32_e32 v81, 1.0, v86
	v_rcp_f32_e32 v86, v81
	v_add_f32_e32 v81, 1.0, v87
	v_pk_mul_f32 v[76:77], v[70:71], v[80:81] op_sel_hi:[1,0]
	v_pk_mul_f32 v[78:79], v[68:69], v[80:81] op_sel_hi:[1,0]
	v_rcp_f32_e32 v87, v81
	v_exp_f32_e32 v78, v78
	v_exp_f32_e32 v79, v79
	v_exp_f32_e32 v80, v76
	v_exp_f32_e32 v81, v77
	v_add_f32_e32 v76, 1.0, v78
	v_add_f32_e32 v77, 1.0, v79
	v_add_f32_e32 v78, 1.0, v80
	v_add_f32_e32 v79, 1.0, v81
	v_rcp_f32_e32 v76, v76
	v_rcp_f32_e32 v77, v77
	v_rcp_f32_e32 v78, v78
	v_rcp_f32_e32 v79, v79
	v_mul_f32_e32 v82, v234, v234
	v_pk_mul_f32 v[64:65], v[64:65], v[82:83] op_sel_hi:[1,0]
	v_pk_mul_f32 v[66:67], v[66:67], v[82:83] op_sel_hi:[1,0]
	v_pk_mul_f32 v[72:73], v[72:73], v[82:83] op_sel_hi:[1,0]
	v_pk_mul_f32 v[74:75], v[74:75], v[82:83] op_sel_hi:[1,0]
	v_pk_mul_f32 v[68:69], v[66:67], v[78:79]
	v_pk_mul_f32 v[66:67], v[64:65], v[76:77]
	v_add_u32_e32 v70, 48, v181
	v_pk_mul_f32 v[74:75], v[74:75], v[86:87]
	v_pk_mul_f32 v[72:73], v[72:73], v[84:85]
	s_nop 0
	v_cvt_pk_bf16_f32 v64, v72, v73
	v_cvt_pk_bf16_f32 v65, v74, v75
	v_cvt_pk_bf16_f32 v66, v66, v67
	v_cvt_pk_bf16_f32 v67, v68, v69
	v_mad_i64_i32 v[68:69], s[0:1], v70, s44, v[112:113]
	v_lshl_add_u64 v[68:69], v[68:69], 0, v[114:115]
	global_store_dwordx4 v[68:69], v[64:67], off
	s_nop 1
	v_add_u32_e32 v65, 0x80, v181
	v_mul_f32_e32 v64, 0xbfb8aa3b, v242
	v_pk_mul_f32 v[70:71], v[60:61], v[64:65] op_sel_hi:[1,0]
	v_pk_mul_f32 v[68:69], v[62:63], v[64:65] op_sel_hi:[1,0]
	v_exp_f32_e32 v67, v70
	v_exp_f32_e32 v70, v71
	v_exp_f32_e32 v71, v68
	v_exp_f32_e32 v72, v69
	v_add_f32_e32 v67, 1.0, v67
	v_rcp_f32_e32 v68, v67
	v_add_f32_e32 v67, 1.0, v70
	v_rcp_f32_e32 v69, v67
	v_add_f32_e32 v67, 1.0, v71
	v_mul_f32_e32 v66, v242, v242
	v_rcp_f32_e32 v70, v67
	v_add_f32_e32 v67, 1.0, v72
	v_pk_mul_f32 v[60:61], v[54:55], v[64:65] op_sel_hi:[1,0]
	v_pk_mul_f32 v[62:63], v[52:53], v[64:65] op_sel_hi:[1,0]
	v_rcp_f32_e32 v71, v67
	v_pk_mul_f32 v[56:57], v[56:57], v[66:67] op_sel_hi:[1,0]
	v_pk_mul_f32 v[58:59], v[58:59], v[66:67] op_sel_hi:[1,0]
	v_exp_f32_e32 v62, v62
	v_exp_f32_e32 v63, v63
	v_exp_f32_e32 v64, v60
	v_exp_f32_e32 v67, v61
	v_add_f32_e32 v60, 1.0, v62
	v_add_f32_e32 v61, 1.0, v63
	v_add_f32_e32 v62, 1.0, v64
	v_add_f32_e32 v63, 1.0, v67
	v_rcp_f32_e32 v60, v60
	v_rcp_f32_e32 v61, v61
	v_rcp_f32_e32 v62, v62
	v_rcp_f32_e32 v63, v63
	v_pk_mul_f32 v[48:49], v[48:49], v[66:67] op_sel_hi:[1,0]
	v_pk_mul_f32 v[50:51], v[50:51], v[66:67] op_sel_hi:[1,0]
	v_pk_mul_f32 v[58:59], v[58:59], v[70:71]
	v_pk_mul_f32 v[52:53], v[50:51], v[62:63]
	v_pk_mul_f32 v[50:51], v[48:49], v[60:61]
	v_pk_mul_f32 v[56:57], v[56:57], v[68:69]
	s_nop 0
	v_cvt_pk_bf16_f32 v48, v56, v57
	v_cvt_pk_bf16_f32 v49, v58, v59
	v_cvt_pk_bf16_f32 v50, v50, v51
	v_cvt_pk_bf16_f32 v51, v52, v53
	v_mad_i64_i32 v[52:53], s[0:1], v65, s44, v[112:113]
	v_lshl_add_u64 v[52:53], v[52:53], 0, v[114:115]
	global_store_dwordx4 v[52:53], v[48:51], off
	s_nop 1
	v_mul_f32_e32 v48, 0xbfb8aa3b, v251
	v_pk_mul_f32 v[54:55], v[44:45], v[48:49] op_sel_hi:[1,0]
	v_pk_mul_f32 v[52:53], v[46:47], v[48:49] op_sel_hi:[1,0]
	v_exp_f32_e32 v49, v54
	v_exp_f32_e32 v51, v55
	v_exp_f32_e32 v54, v52
	v_exp_f32_e32 v55, v53
	v_add_f32_e32 v49, 1.0, v49
	v_rcp_f32_e32 v52, v49
	v_add_f32_e32 v49, 1.0, v51
	v_rcp_f32_e32 v53, v49
	v_add_f32_e32 v49, 1.0, v54
	v_rcp_f32_e32 v54, v49
	v_add_f32_e32 v49, 1.0, v55
	v_pk_mul_f32 v[44:45], v[38:39], v[48:49] op_sel_hi:[1,0]
	v_pk_mul_f32 v[46:47], v[36:37], v[48:49] op_sel_hi:[1,0]
	v_rcp_f32_e32 v55, v49
	v_exp_f32_e32 v46, v46
	v_exp_f32_e32 v47, v47
	v_exp_f32_e32 v48, v44
	v_exp_f32_e32 v49, v45
	v_add_f32_e32 v44, 1.0, v46
	v_add_f32_e32 v45, 1.0, v47
	v_add_f32_e32 v46, 1.0, v48
	v_add_f32_e32 v47, 1.0, v49
	v_rcp_f32_e32 v44, v44
	v_rcp_f32_e32 v45, v45
	v_rcp_f32_e32 v46, v46
	v_rcp_f32_e32 v47, v47
	v_mul_f32_e32 v50, v251, v251
	v_pk_mul_f32 v[32:33], v[32:33], v[50:51] op_sel_hi:[1,0]
	v_pk_mul_f32 v[34:35], v[34:35], v[50:51] op_sel_hi:[1,0]
	v_pk_mul_f32 v[40:41], v[40:41], v[50:51] op_sel_hi:[1,0]
	v_pk_mul_f32 v[42:43], v[42:43], v[50:51] op_sel_hi:[1,0]
	v_pk_mul_f32 v[36:37], v[34:35], v[46:47]
	v_pk_mul_f32 v[34:35], v[32:33], v[44:45]
	v_add_u32_e32 v38, 0x90, v181
	v_pk_mul_f32 v[42:43], v[42:43], v[54:55]
	v_pk_mul_f32 v[40:41], v[40:41], v[52:53]
	s_nop 0
	v_cvt_pk_bf16_f32 v32, v40, v41
	v_cvt_pk_bf16_f32 v33, v42, v43
	v_cvt_pk_bf16_f32 v34, v34, v35
	v_cvt_pk_bf16_f32 v35, v36, v37
	v_mad_i64_i32 v[36:37], s[0:1], v38, s44, v[112:113]
	v_lshl_add_u64 v[36:37], v[36:37], 0, v[114:115]
	global_store_dwordx4 v[36:37], v[32:35], off
	s_nop 1
	v_mul_f32_e32 v32, 0xbfb8aa3b, v243
	v_pk_mul_f32 v[38:39], v[28:29], v[32:33] op_sel_hi:[1,0]
	v_pk_mul_f32 v[36:37], v[30:31], v[32:33] op_sel_hi:[1,0]
	v_exp_f32_e32 v33, v38
	v_exp_f32_e32 v35, v39
	v_exp_f32_e32 v38, v36
	v_exp_f32_e32 v39, v37
	v_add_f32_e32 v33, 1.0, v33
	v_rcp_f32_e32 v36, v33
	v_add_f32_e32 v33, 1.0, v35
	v_rcp_f32_e32 v37, v33
	v_add_f32_e32 v33, 1.0, v38
	v_rcp_f32_e32 v38, v33
	v_add_f32_e32 v33, 1.0, v39
	v_pk_mul_f32 v[28:29], v[22:23], v[32:33] op_sel_hi:[1,0]
	v_pk_mul_f32 v[30:31], v[20:21], v[32:33] op_sel_hi:[1,0]
	v_rcp_f32_e32 v39, v33
	v_exp_f32_e32 v30, v30
	v_exp_f32_e32 v31, v31
	v_exp_f32_e32 v32, v28
	v_exp_f32_e32 v33, v29
	v_add_f32_e32 v28, 1.0, v30
	v_add_f32_e32 v29, 1.0, v31
	v_add_f32_e32 v30, 1.0, v32
	v_add_f32_e32 v31, 1.0, v33
	v_rcp_f32_e32 v28, v28
	v_rcp_f32_e32 v29, v29
	v_rcp_f32_e32 v30, v30
	v_rcp_f32_e32 v31, v31
	v_mul_f32_e32 v34, v243, v243
	v_pk_mul_f32 v[16:17], v[16:17], v[34:35] op_sel_hi:[1,0]
	v_pk_mul_f32 v[18:19], v[18:19], v[34:35] op_sel_hi:[1,0]
	v_pk_mul_f32 v[24:25], v[24:25], v[34:35] op_sel_hi:[1,0]
	v_pk_mul_f32 v[26:27], v[26:27], v[34:35] op_sel_hi:[1,0]
	v_pk_mul_f32 v[20:21], v[18:19], v[30:31]
	v_pk_mul_f32 v[18:19], v[16:17], v[28:29]
	v_add_u32_e32 v22, 0xa0, v181
	v_pk_mul_f32 v[26:27], v[26:27], v[38:39]
	v_pk_mul_f32 v[24:25], v[24:25], v[36:37]
	s_nop 0
	v_cvt_pk_bf16_f32 v16, v24, v25
	v_cvt_pk_bf16_f32 v17, v26, v27
	v_cvt_pk_bf16_f32 v18, v18, v19
	v_cvt_pk_bf16_f32 v19, v20, v21
	v_mad_i64_i32 v[20:21], s[0:1], v22, s44, v[112:113]
	v_lshl_add_u64 v[20:21], v[20:21], 0, v[114:115]
	global_store_dwordx4 v[20:21], v[16:19], off
	s_nop 1
	v_mul_f32_e32 v16, 0xbfb8aa3b, v248
	v_pk_mul_f32 v[22:23], v[12:13], v[16:17] op_sel_hi:[1,0]
	v_pk_mul_f32 v[20:21], v[14:15], v[16:17] op_sel_hi:[1,0]
	v_exp_f32_e32 v17, v22
	v_exp_f32_e32 v19, v23
	v_exp_f32_e32 v22, v20
	v_exp_f32_e32 v23, v21
	v_add_f32_e32 v17, 1.0, v17
	v_rcp_f32_e32 v20, v17
	v_add_f32_e32 v17, 1.0, v19
	v_rcp_f32_e32 v21, v17
	v_add_f32_e32 v17, 1.0, v22
	v_rcp_f32_e32 v22, v17
	v_add_f32_e32 v17, 1.0, v23
	v_pk_mul_f32 v[12:13], v[6:7], v[16:17] op_sel_hi:[1,0]
	v_pk_mul_f32 v[14:15], v[4:5], v[16:17] op_sel_hi:[1,0]
	v_rcp_f32_e32 v23, v17
	v_exp_f32_e32 v14, v14
	v_exp_f32_e32 v15, v15
	v_exp_f32_e32 v16, v12
	v_exp_f32_e32 v17, v13
	v_add_f32_e32 v12, 1.0, v14
	v_add_f32_e32 v13, 1.0, v15
	v_add_f32_e32 v14, 1.0, v16
	v_add_f32_e32 v15, 1.0, v17
	v_rcp_f32_e32 v12, v12
	v_rcp_f32_e32 v13, v13
	v_rcp_f32_e32 v14, v14
	v_rcp_f32_e32 v15, v15
	v_mul_f32_e32 v18, v248, v248
	v_pk_mul_f32 v[0:1], v[0:1], v[18:19] op_sel_hi:[1,0]
	v_pk_mul_f32 v[2:3], v[2:3], v[18:19] op_sel_hi:[1,0]
	v_pk_mul_f32 v[8:9], v[8:9], v[18:19] op_sel_hi:[1,0]
	v_pk_mul_f32 v[10:11], v[10:11], v[18:19] op_sel_hi:[1,0]
	v_pk_mul_f32 v[4:5], v[2:3], v[14:15]
	v_pk_mul_f32 v[2:3], v[0:1], v[12:13]
	v_add_u32_e32 v6, 0xb0, v181
	v_pk_mul_f32 v[10:11], v[10:11], v[22:23]
	v_pk_mul_f32 v[8:9], v[8:9], v[20:21]
	s_nop 0
	v_cvt_pk_bf16_f32 v0, v8, v9
	v_cvt_pk_bf16_f32 v1, v10, v11
	v_cvt_pk_bf16_f32 v2, v2, v3
	v_cvt_pk_bf16_f32 v3, v4, v5
	v_mad_i64_i32 v[4:5], s[0:1], v6, s44, v[112:113]
	v_lshl_add_u64 v[4:5], v[4:5], 0, v[114:115]
	s_mov_b64 s[0:1], -1
	global_store_dwordx4 v[4:5], v[0:3], off
	s_cbranch_vccnz .LBB0_1360
	s_andn2_b64 vcc, exec, s[8:9]
	s_cbranch_vccnz .LBB0_1359
	s_barrier
	s_branch .LBB0_1359
